# MODE_IN (no activation) epilogue: coalesced lane-transposed stores as in MODE_UP
# speedup vs baseline: 1.0239x; 1.0069x over previous
; __device__ __forceinline__ float sigm(float v) { return __builtin_amdgcn_rcpf(1.0f + __builtin_amdgcn_exp2f(-1.44269504089f * v)); }
; __device__ __forceinline__ u32x4 pack8(const f32x4& v0, const f32x4& v1) { u32x4 w; w.x = cvt_pk_bf16(v0[0], v0[1]); w.y = cvt_pk_bf16(v0[2], v0[3]); w.z = cvt_pk_bf16(v1[0], v1[1]); w.w = cvt_pk_bf16(v1[2], v1[3]); return w; }
; __device__ __forceinline__ float sumsq8(const f32x4& v0, const f32x4& v1) { return (v0[0] * v0[0] + v0[1] * v0[1]) + (v0[2] * v0[2] + v0[3] * v0[3]) + (v1[0] * v1[0] + v1[1] * v1[1]) + (v1[2] * v1[2] + v1[3] * v1[3]); }
; template <int ACT> __device__ __forceinline__ void epi_act_store(f32x4 (&acc)[2][2][4][2], const float (&rs)[2][4], bf16_t* out, int ld, int row0, int col0, float* ssqv_slot, bool want_ssq, int fq) {
;     ...
;         for (int m = 0; m < 4; ++m) { const int row = row0 + ai * 128 + m * 16; float sq = 0.f;
; #pragma unroll
;             for (int bj = 0; bj < 2; ++bj) { f32x4 v0 = acc[ai][bj][m][0] * rs[ai][m], v1 = acc[ai][bj][m][1] * rs[ai][m];
;                 if (ACT == 1) { f32x2 a = gelu_pk((f32x2){v0[0], v0[1]}), b = gelu_pk((f32x2){v0[2], v0[3]}), c = gelu_pk((f32x2){v1[0], v1[1]}), d = gelu_pk((f32x2){v1[2], v1[3]});
;                     v0 = (f32x4){a.x, a.y, b.x, b.y}; v1 = (f32x4){c.x, c.y, d.x, d.y}; sq += sumsq8(v0, v1); }
;                 if (ACT == 2) {
; #pragma unroll
;                     for (int e = 0; e < 4; ++e) { v0[e] = sigm(v0[e]); v1[e] = sigm(v1[e]); } }
;                 *(u32x4*)(out + (size_t)row * ld + col0 + bj * 128) = pack8(v0, v1); }
; __device__ __forceinline__ void epi_run(const Epi& E, f32x4 (&acc)[2][2][4][2], const Unit& u, int wr, int wc, int fr, int fq) {
;     ...
;     if (mode == MODE_IN || mode == MODE_UP) {
;         float rs[2][4]; epi_rstd(E.ssq_in, row0, fq, rs);
;         if (mode == MODE_UP) { epi_act_store<0>(acc, rs, E.out16, E.ld16, row0, col0, nullptr, false, fq); return; }
;         const int atype = u.pn >> 2;
;         if (atype == 2) epi_act_store<1>(acc, rs, E.Z, NIN, row0, col0, E.ssqv + (size_t)((u.pn - 8) * 4 + wc) * M, true, fq);
;         else epi_act_store<0>(acc, rs, E.Z, NIN, row0, col0, nullptr, false, fq);
.Lmy_rstd_join:
	s_cbranch_scc0 .LBB0_349
	s_and_b32 s2, s23, -4
	s_cmp_lg_u32 s2, 8
	s_cbranch_scc0 .LBB0_330
	s_waitcnt lgkmcnt(0)
	v_lshrrev_b32_e32 v214, 2, v201
	v_and_b32_e32 v215, 3, v201
	v_lshl_add_u32 v216, v215, 4, v214
	v_lshlrev_b32_e32 v216, 2, v216
	v_and_b32_e32 v217, -16, v239
	v_or_b32_e32 v217, v217, v214
	v_lshl_add_u32 v217, s95, 8, v217
	v_and_b32_e32 v218, 0xffffffe7, v242
	v_lshl_or_b32 v218, v215, 3, v218
	v_lshl_or_b32 v218, s23, 8, v218
	v_mul_lo_u32 v222, v217, s69
	v_lshl_add_u32 v222, v218, 1, v222
	v_mov_b32_e32 v223, 0
	v_lshl_add_u64 v[220:221], v[222:223], 0, s[70:71]
	s_lshl_b32 s96, s69, 4
	s_mov_b32 s97, 0
	s_mul_i32 s44, s69, 0x50
	s_mov_b32 s45, 0
	v_pk_mul_f32 v[126:127], v[126:127], v[130:131] op_sel_hi:[1,0]
	v_pk_mul_f32 v[128:129], v[128:129], v[130:131] op_sel_hi:[1,0]
	v_pk_mul_f32 v[122:123], v[122:123], v[130:131] op_sel_hi:[1,0]
	v_pk_mul_f32 v[124:125], v[124:125], v[130:131] op_sel_hi:[1,0]
	v_cvt_pk_bf16_f32 v126, v126, v127
	v_cvt_pk_bf16_f32 v127, v128, v129
	v_cvt_pk_bf16_f32 v128, v122, v123
	v_cvt_pk_bf16_f32 v129, v124, v125
	ds_bpermute_b32 v224, v216, v126
	ds_bpermute_b32 v225, v216, v127
	ds_bpermute_b32 v226, v216, v128
	ds_bpermute_b32 v227, v216, v129
	v_pk_mul_f32 v[118:119], v[118:119], v[130:131] op_sel_hi:[1,0]
	v_pk_mul_f32 v[120:121], v[120:121], v[130:131] op_sel_hi:[1,0]
	v_pk_mul_f32 v[114:115], v[114:115], v[130:131] op_sel_hi:[1,0]
	v_pk_mul_f32 v[116:117], v[116:117], v[130:131] op_sel_hi:[1,0]
	v_cvt_pk_bf16_f32 v118, v118, v119
	v_cvt_pk_bf16_f32 v119, v120, v121
	v_cvt_pk_bf16_f32 v120, v114, v115
	v_cvt_pk_bf16_f32 v121, v116, v117
	ds_bpermute_b32 v228, v216, v118
	ds_bpermute_b32 v229, v216, v119
	ds_bpermute_b32 v230, v216, v120
	ds_bpermute_b32 v231, v216, v121
	s_waitcnt lgkmcnt(4)
	global_store_dwordx4 v[220:221], v[224:227], off
	v_pk_mul_f32 v[110:111], v[110:111], v[0:1] op_sel_hi:[1,0]
	v_pk_mul_f32 v[112:113], v[112:113], v[0:1] op_sel_hi:[1,0]
	v_pk_mul_f32 v[106:107], v[106:107], v[0:1] op_sel_hi:[1,0]
	v_pk_mul_f32 v[108:109], v[108:109], v[0:1] op_sel_hi:[1,0]
	v_cvt_pk_bf16_f32 v110, v110, v111
	v_cvt_pk_bf16_f32 v111, v112, v113
	v_cvt_pk_bf16_f32 v112, v106, v107
	v_cvt_pk_bf16_f32 v113, v108, v109
	ds_bpermute_b32 v224, v216, v110
	ds_bpermute_b32 v225, v216, v111
	ds_bpermute_b32 v226, v216, v112
	ds_bpermute_b32 v227, v216, v113
	s_waitcnt lgkmcnt(4)
	global_store_dwordx4 v[220:221], v[228:231], off offset:256
	v_lshl_add_u64 v[220:221], v[220:221], 0, s[96:97]
	v_pk_mul_f32 v[102:103], v[102:103], v[0:1] op_sel_hi:[1,0]
	v_pk_mul_f32 v[104:105], v[104:105], v[0:1] op_sel_hi:[1,0]
	v_pk_mul_f32 v[94:95], v[94:95], v[0:1] op_sel_hi:[1,0]
	v_pk_mul_f32 v[96:97], v[96:97], v[0:1] op_sel_hi:[1,0]
	v_cvt_pk_bf16_f32 v102, v102, v103
	v_cvt_pk_bf16_f32 v103, v104, v105
	v_cvt_pk_bf16_f32 v104, v94, v95
	v_cvt_pk_bf16_f32 v105, v96, v97
	ds_bpermute_b32 v228, v216, v102
	ds_bpermute_b32 v229, v216, v103
	ds_bpermute_b32 v230, v216, v104
	ds_bpermute_b32 v231, v216, v105
	s_waitcnt lgkmcnt(4)
	global_store_dwordx4 v[220:221], v[224:227], off
	v_pk_mul_f32 v[98:99], v[98:99], v[132:133] op_sel_hi:[1,0]
	v_pk_mul_f32 v[100:101], v[100:101], v[132:133] op_sel_hi:[1,0]
	v_pk_mul_f32 v[90:91], v[90:91], v[132:133] op_sel_hi:[1,0]
	v_pk_mul_f32 v[92:93], v[92:93], v[132:133] op_sel_hi:[1,0]
	v_cvt_pk_bf16_f32 v98, v98, v99
	v_cvt_pk_bf16_f32 v99, v100, v101
	v_cvt_pk_bf16_f32 v100, v90, v91
	v_cvt_pk_bf16_f32 v101, v92, v93
	ds_bpermute_b32 v224, v216, v98
	ds_bpermute_b32 v225, v216, v99
	ds_bpermute_b32 v226, v216, v100
	ds_bpermute_b32 v227, v216, v101
	s_waitcnt lgkmcnt(4)
	global_store_dwordx4 v[220:221], v[228:231], off offset:256
	v_lshl_add_u64 v[220:221], v[220:221], 0, s[96:97]
	v_pk_mul_f32 v[86:87], v[86:87], v[132:133] op_sel_hi:[1,0]
	v_pk_mul_f32 v[88:89], v[88:89], v[132:133] op_sel_hi:[1,0]
	v_pk_mul_f32 v[78:79], v[78:79], v[132:133] op_sel_hi:[1,0]
	v_pk_mul_f32 v[80:81], v[80:81], v[132:133] op_sel_hi:[1,0]
	v_cvt_pk_bf16_f32 v86, v86, v87
	v_cvt_pk_bf16_f32 v87, v88, v89
	v_cvt_pk_bf16_f32 v88, v78, v79
	v_cvt_pk_bf16_f32 v89, v80, v81
	ds_bpermute_b32 v228, v216, v86
	ds_bpermute_b32 v229, v216, v87
	ds_bpermute_b32 v230, v216, v88
	ds_bpermute_b32 v231, v216, v89
	s_waitcnt lgkmcnt(4)
	global_store_dwordx4 v[220:221], v[224:227], off
	v_pk_mul_f32 v[82:83], v[82:83], v[142:143] op_sel_hi:[1,0]
	v_pk_mul_f32 v[84:85], v[84:85], v[142:143] op_sel_hi:[1,0]
	v_pk_mul_f32 v[74:75], v[74:75], v[142:143] op_sel_hi:[1,0]
	v_pk_mul_f32 v[76:77], v[76:77], v[142:143] op_sel_hi:[1,0]
	v_cvt_pk_bf16_f32 v82, v82, v83
	v_cvt_pk_bf16_f32 v83, v84, v85
	v_cvt_pk_bf16_f32 v84, v74, v75
	v_cvt_pk_bf16_f32 v85, v76, v77
	ds_bpermute_b32 v224, v216, v82
	ds_bpermute_b32 v225, v216, v83
	ds_bpermute_b32 v226, v216, v84
	ds_bpermute_b32 v227, v216, v85
	s_waitcnt lgkmcnt(4)
	global_store_dwordx4 v[220:221], v[228:231], off offset:256
	v_lshl_add_u64 v[220:221], v[220:221], 0, s[96:97]
	v_pk_mul_f32 v[70:71], v[70:71], v[142:143] op_sel_hi:[1,0]
	v_pk_mul_f32 v[72:73], v[72:73], v[142:143] op_sel_hi:[1,0]
	v_pk_mul_f32 v[66:67], v[66:67], v[142:143] op_sel_hi:[1,0]
	v_pk_mul_f32 v[68:69], v[68:69], v[142:143] op_sel_hi:[1,0]
	v_cvt_pk_bf16_f32 v70, v70, v71
	v_cvt_pk_bf16_f32 v71, v72, v73
	v_cvt_pk_bf16_f32 v72, v66, v67
	v_cvt_pk_bf16_f32 v73, v68, v69
	ds_bpermute_b32 v228, v216, v70
	ds_bpermute_b32 v229, v216, v71
	ds_bpermute_b32 v230, v216, v72
	ds_bpermute_b32 v231, v216, v73
	s_waitcnt lgkmcnt(4)
; __device__ __forceinline__ float sigm(float v) { return __builtin_amdgcn_rcpf(1.0f + __builtin_amdgcn_exp2f(-1.44269504089f * v)); }
; __device__ __forceinline__ u32x4 pack8(const f32x4& v0, const f32x4& v1) { u32x4 w; w.x = cvt_pk_bf16(v0[0], v0[1]); w.y = cvt_pk_bf16(v0[2], v0[3]); w.z = cvt_pk_bf16(v1[0], v1[1]); w.w = cvt_pk_bf16(v1[2], v1[3]); return w; }
; __device__ __forceinline__ float sumsq8(const f32x4& v0, const f32x4& v1) { return (v0[0] * v0[0] + v0[1] * v0[1]) + (v0[2] * v0[2] + v0[3] * v0[3]) + (v1[0] * v1[0] + v1[1] * v1[1]) + (v1[2] * v1[2] + v1[3] * v1[3]); }
; template <int ACT> __device__ __forceinline__ void epi_act_store(f32x4 (&acc)[2][2][4][2], const float (&rs)[2][4], bf16_t* out, int ld, int row0, int col0, float* ssqv_slot, bool want_ssq, int fq) {
;     ...
;         for (int m = 0; m < 4; ++m) { const int row = row0 + ai * 128 + m * 16; float sq = 0.f;
; #pragma unroll
;             for (int bj = 0; bj < 2; ++bj) { f32x4 v0 = acc[ai][bj][m][0] * rs[ai][m], v1 = acc[ai][bj][m][1] * rs[ai][m];
;                 if (ACT == 1) { f32x2 a = gelu_pk((f32x2){v0[0], v0[1]}), b = gelu_pk((f32x2){v0[2], v0[3]}), c = gelu_pk((f32x2){v1[0], v1[1]}), d = gelu_pk((f32x2){v1[2], v1[3]});
;                     v0 = (f32x4){a.x, a.y, b.x, b.y}; v1 = (f32x4){c.x, c.y, d.x, d.y}; sq += sumsq8(v0, v1); }
;                 if (ACT == 2) {
; #pragma unroll
;                     for (int e = 0; e < 4; ++e) { v0[e] = sigm(v0[e]); v1[e] = sigm(v1[e]); } }
;                 *(u32x4*)(out + (size_t)row * ld + col0 + bj * 128) = pack8(v0, v1); }
; __device__ __forceinline__ void epi_run(const Epi& E, f32x4 (&acc)[2][2][4][2], const Unit& u, int wr, int wc, int fr, int fq) {
;     ...
;     if (mode == MODE_IN || mode == MODE_UP) {
;         float rs[2][4]; epi_rstd(E.ssq_in, row0, fq, rs);
;         if (mode == MODE_UP) { epi_act_store<0>(acc, rs, E.out16, E.ld16, row0, col0, nullptr, false, fq); return; }
;         const int atype = u.pn >> 2;
;         if (atype == 2) epi_act_store<1>(acc, rs, E.Z, NIN, row0, col0, E.ssqv + (size_t)((u.pn - 8) * 4 + wc) * M, true, fq);
;         else epi_act_store<0>(acc, rs, E.Z, NIN, row0, col0, nullptr, false, fq);
	global_store_dwordx4 v[220:221], v[224:227], off
	v_pk_mul_f32 v[62:63], v[62:63], v[140:141] op_sel_hi:[1,0]
	v_pk_mul_f32 v[64:65], v[64:65], v[140:141] op_sel_hi:[1,0]
	v_pk_mul_f32 v[58:59], v[58:59], v[140:141] op_sel_hi:[1,0]
	v_pk_mul_f32 v[60:61], v[60:61], v[140:141] op_sel_hi:[1,0]
	v_cvt_pk_bf16_f32 v62, v62, v63
	v_cvt_pk_bf16_f32 v63, v64, v65
	v_cvt_pk_bf16_f32 v64, v58, v59
	v_cvt_pk_bf16_f32 v65, v60, v61
	ds_bpermute_b32 v224, v216, v62
	ds_bpermute_b32 v225, v216, v63
	ds_bpermute_b32 v226, v216, v64
	ds_bpermute_b32 v227, v216, v65
	s_waitcnt lgkmcnt(4)
	global_store_dwordx4 v[220:221], v[228:231], off offset:256
	v_lshl_add_u64 v[220:221], v[220:221], 0, s[44:45]
	v_pk_mul_f32 v[54:55], v[54:55], v[140:141] op_sel_hi:[1,0]
	v_pk_mul_f32 v[56:57], v[56:57], v[140:141] op_sel_hi:[1,0]
	v_pk_mul_f32 v[50:51], v[50:51], v[140:141] op_sel_hi:[1,0]
	v_pk_mul_f32 v[52:53], v[52:53], v[140:141] op_sel_hi:[1,0]
	v_cvt_pk_bf16_f32 v54, v54, v55
	v_cvt_pk_bf16_f32 v55, v56, v57
	v_cvt_pk_bf16_f32 v56, v50, v51
	v_cvt_pk_bf16_f32 v57, v52, v53
	ds_bpermute_b32 v228, v216, v54
	ds_bpermute_b32 v229, v216, v55
	ds_bpermute_b32 v230, v216, v56
	ds_bpermute_b32 v231, v216, v57
	s_waitcnt lgkmcnt(4)
	global_store_dwordx4 v[220:221], v[224:227], off
	v_pk_mul_f32 v[46:47], v[46:47], v[138:139] op_sel_hi:[1,0]
	v_pk_mul_f32 v[48:49], v[48:49], v[138:139] op_sel_hi:[1,0]
	v_pk_mul_f32 v[42:43], v[42:43], v[138:139] op_sel_hi:[1,0]
	v_pk_mul_f32 v[44:45], v[44:45], v[138:139] op_sel_hi:[1,0]
	v_cvt_pk_bf16_f32 v46, v46, v47
	v_cvt_pk_bf16_f32 v47, v48, v49
	v_cvt_pk_bf16_f32 v48, v42, v43
	v_cvt_pk_bf16_f32 v49, v44, v45
	ds_bpermute_b32 v224, v216, v46
	ds_bpermute_b32 v225, v216, v47
	ds_bpermute_b32 v226, v216, v48
	ds_bpermute_b32 v227, v216, v49
	s_waitcnt lgkmcnt(4)
	global_store_dwordx4 v[220:221], v[228:231], off offset:256
	v_lshl_add_u64 v[220:221], v[220:221], 0, s[96:97]
	v_pk_mul_f32 v[38:39], v[38:39], v[138:139] op_sel_hi:[1,0]
	v_pk_mul_f32 v[40:41], v[40:41], v[138:139] op_sel_hi:[1,0]
	v_pk_mul_f32 v[34:35], v[34:35], v[138:139] op_sel_hi:[1,0]
	v_pk_mul_f32 v[36:37], v[36:37], v[138:139] op_sel_hi:[1,0]
	v_cvt_pk_bf16_f32 v38, v38, v39
	v_cvt_pk_bf16_f32 v39, v40, v41
	v_cvt_pk_bf16_f32 v40, v34, v35
	v_cvt_pk_bf16_f32 v41, v36, v37
	ds_bpermute_b32 v228, v216, v38
	ds_bpermute_b32 v229, v216, v39
	ds_bpermute_b32 v230, v216, v40
	ds_bpermute_b32 v231, v216, v41
	s_waitcnt lgkmcnt(4)
	global_store_dwordx4 v[220:221], v[224:227], off
	v_pk_mul_f32 v[30:31], v[30:31], v[134:135] op_sel_hi:[1,0]
	v_pk_mul_f32 v[32:33], v[32:33], v[134:135] op_sel_hi:[1,0]
	v_pk_mul_f32 v[26:27], v[26:27], v[134:135] op_sel_hi:[1,0]
	v_pk_mul_f32 v[28:29], v[28:29], v[134:135] op_sel_hi:[1,0]
	v_cvt_pk_bf16_f32 v30, v30, v31
	v_cvt_pk_bf16_f32 v31, v32, v33
	v_cvt_pk_bf16_f32 v32, v26, v27
	v_cvt_pk_bf16_f32 v33, v28, v29
	ds_bpermute_b32 v224, v216, v30
	ds_bpermute_b32 v225, v216, v31
	ds_bpermute_b32 v226, v216, v32
	ds_bpermute_b32 v227, v216, v33
	s_waitcnt lgkmcnt(4)
	global_store_dwordx4 v[220:221], v[228:231], off offset:256
	v_lshl_add_u64 v[220:221], v[220:221], 0, s[96:97]
	v_pk_mul_f32 v[22:23], v[22:23], v[134:135] op_sel_hi:[1,0]
	v_pk_mul_f32 v[24:25], v[24:25], v[134:135] op_sel_hi:[1,0]
	v_pk_mul_f32 v[18:19], v[18:19], v[134:135] op_sel_hi:[1,0]
	v_pk_mul_f32 v[20:21], v[20:21], v[134:135] op_sel_hi:[1,0]
	v_cvt_pk_bf16_f32 v22, v22, v23
	v_cvt_pk_bf16_f32 v23, v24, v25
	v_cvt_pk_bf16_f32 v24, v18, v19
	v_cvt_pk_bf16_f32 v25, v20, v21
	ds_bpermute_b32 v228, v216, v22
	ds_bpermute_b32 v229, v216, v23
	ds_bpermute_b32 v230, v216, v24
	ds_bpermute_b32 v231, v216, v25
	s_waitcnt lgkmcnt(4)
	global_store_dwordx4 v[220:221], v[224:227], off
	v_pk_mul_f32 v[14:15], v[14:15], v[136:137] op_sel_hi:[1,0]
	v_pk_mul_f32 v[16:17], v[16:17], v[136:137] op_sel_hi:[1,0]
	v_pk_mul_f32 v[10:11], v[10:11], v[136:137] op_sel_hi:[1,0]
	v_pk_mul_f32 v[12:13], v[12:13], v[136:137] op_sel_hi:[1,0]
	v_cvt_pk_bf16_f32 v14, v14, v15
	v_cvt_pk_bf16_f32 v15, v16, v17
	v_cvt_pk_bf16_f32 v16, v10, v11
	v_cvt_pk_bf16_f32 v17, v12, v13
	ds_bpermute_b32 v224, v216, v14
	ds_bpermute_b32 v225, v216, v15
	ds_bpermute_b32 v226, v216, v16
	ds_bpermute_b32 v227, v216, v17
	s_waitcnt lgkmcnt(4)
	global_store_dwordx4 v[220:221], v[228:231], off offset:256
	v_lshl_add_u64 v[220:221], v[220:221], 0, s[96:97]
	v_pk_mul_f32 v[6:7], v[6:7], v[136:137] op_sel_hi:[1,0]
	v_pk_mul_f32 v[8:9], v[8:9], v[136:137] op_sel_hi:[1,0]
	v_pk_mul_f32 v[2:3], v[2:3], v[136:137] op_sel_hi:[1,0]
	v_pk_mul_f32 v[4:5], v[4:5], v[136:137] op_sel_hi:[1,0]
	v_cvt_pk_bf16_f32 v6, v6, v7
	v_cvt_pk_bf16_f32 v7, v8, v9
	v_cvt_pk_bf16_f32 v8, v2, v3
	v_cvt_pk_bf16_f32 v9, v4, v5
	ds_bpermute_b32 v228, v216, v6
	ds_bpermute_b32 v229, v216, v7
	ds_bpermute_b32 v230, v216, v8
	ds_bpermute_b32 v231, v216, v9
	s_waitcnt lgkmcnt(4)
	global_store_dwordx4 v[220:221], v[224:227], off
	s_waitcnt lgkmcnt(0)
	global_store_dwordx4 v[220:221], v[228:231], off offset:256
	s_mov_b64 s[8:9], 0
